# v37 + per-quarter (4x finer) alternating priority in S5 final loop
# baseline (speedup 1.0000x reference)
.LBB0_721:
	v_lshl_or_b32 v103, s2, 4, v97
	v_mov_b32_e32 v80, v89
	s_and_saveexec_b64 s[6:7], s[0:1]
	v_sub_u32_e32 v80, 0x8ff, v103
	s_or_b64 exec, exec, s[6:7]
	s_add_i32 s9, s10, 4
	s_min_u32 s11, s9, 0x8b
	s_add_i32 s11, s11, 4
	v_lshl_or_b32 v29, s11, 4, v97
	s_and_saveexec_b64 s[6:7], s[0:1]
	s_xor_b64 s[6:7], exec, s[6:7]
	v_sub_u32_e32 v30, 0x8ff, v29
	s_or_saveexec_b64 s[6:7], s[6:7]
	v_lshl_add_u32 v28, s11, 4, v90
	s_xor_b64 exec, exec, s[6:7]
	v_lshl_add_u32 v30, s11, 4, v90
	s_or_b64 exec, exec, s[6:7]
	v_add_u32_e32 v30, v30, v99
	v_ashrrev_i32_e32 v31, 31, v30
	v_lshlrev_b64 v[30:31], 5, v[30:31]
	v_lshl_add_u64 v[30:31], v[64:65], 0, v[30:31]
	global_load_dwordx2 v[62:63], v[30:31], off
	v_mfma_f32_16x16x16_bf16 v[44:47], v[70:71], v[86:87], 0
	v_add_u32_e32 v91, 0x800, v100
	v_add_u32_e32 v102, 0x2400, v101
	v_mfma_f32_16x16x16_bf16 v[92:95], v[72:73], v[86:87], 0
	v_mfma_f32_16x16x16_bf16 v[104:107], v[74:75], v[86:87], 0
	s_nop 3
	ds_write_b128 v98, v[44:47]
	v_mfma_f32_16x16x16_bf16 v[108:111], v[76:77], v[86:87], 0
	s_nop 0
	ds_write_b128 v98, v[92:95] offset:64
	ds_write_b128 v98, v[104:107] offset:128
	s_nop 4
	ds_write_b128 v98, v[108:111] offset:192
	v_mfma_f32_16x16x16_bf16 v[112:115], v[78:79], v[86:87], 0
	v_mfma_f32_16x16x16_bf16 v[44:47], v[48:49], v[86:87], 0
	v_mfma_f32_16x16x16_bf16 v[92:95], v[50:51], v[86:87], 0
	s_nop 5
	ds_write_b128 v98, v[112:115] offset:256
	ds_write_b128 v98, v[44:47] offset:320
	ds_write_b128 v98, v[92:95] offset:384
	v_add_u32_e32 v92, 0x1000, v100
	v_mfma_f32_16x16x16_bf16 v[44:47], v[52:53], v[86:87], 0
	v_add_u32_e32 v93, 0x1800, v100
	v_add_u32_e32 v94, 0x2000, v101
	v_add_u32_e32 v95, 0x2200, v101
	s_nop 4
	ds_write_b128 v98, v[44:47] offset:448
	s_waitcnt lgkmcnt(0)
	ds_read2_b64 v[44:47], v100 offset1:66
	ds_read2_b64 v[104:107], v100 offset0:132 offset1:198
	ds_read2_b64 v[108:111], v91 offset0:8 offset1:74
	ds_read2_b64 v[112:115], v91 offset0:140 offset1:206
	ds_read2_b64 v[116:119], v92 offset0:16 offset1:82
	ds_read2_b64 v[120:123], v92 offset0:148 offset1:214
	ds_read2_b64 v[124:127], v93 offset0:24 offset1:90
	ds_read2_b64 v[128:131], v93 offset0:156 offset1:222
	s_waitcnt lgkmcnt(7)
	v_pk_fma_f32 v[30:31], v[68:69], v[84:85], v[44:45]
	s_nop 0
	v_pk_fma_f32 v[30:31], v[66:67], v[84:85], v[30:31] op_sel:[0,1,0] op_sel_hi:[1,0,1]
	s_nop 0
	v_pk_fma_f32 v[44:45], v[68:69], v[30:31], v[46:47]
	v_cvt_pk_bf16_f32 v81, v30, v31
	v_pk_fma_f32 v[30:31], v[66:67], v[30:31], v[44:45] op_sel:[0,1,0] op_sel_hi:[1,0,1]
	s_nop 0
	v_cvt_pk_bf16_f32 v44, v30, v31
	ds_write2_b32 v94, v81, v44 offset0:64 offset1:132
	s_waitcnt lgkmcnt(7)
	v_pk_fma_f32 v[44:45], v[68:69], v[30:31], v[104:105]
	v_add_u32_e32 v104, 0x2600, v101
	v_pk_fma_f32 v[30:31], v[66:67], v[30:31], v[44:45] op_sel:[0,1,0] op_sel_hi:[1,0,1]
	v_add_u32_e32 v105, 0x2800, v101
	v_pk_fma_f32 v[44:45], v[68:69], v[30:31], v[106:107]
	v_cvt_pk_bf16_f32 v46, v30, v31
	v_pk_fma_f32 v[30:31], v[66:67], v[30:31], v[44:45] op_sel:[0,1,0] op_sel_hi:[1,0,1]
	v_add_u32_e32 v106, 0x2a00, v101
	v_cvt_pk_bf16_f32 v44, v30, v31
	ds_write2_b32 v95, v46, v44 offset0:72 offset1:140
	s_waitcnt lgkmcnt(7)
	v_pk_fma_f32 v[44:45], v[68:69], v[30:31], v[108:109]
	v_add_u32_e32 v107, 0x2c00, v101
	v_pk_fma_f32 v[30:31], v[66:67], v[30:31], v[44:45] op_sel:[0,1,0] op_sel_hi:[1,0,1]
	v_add_u32_e32 v108, 0x2e00, v101
	v_pk_fma_f32 v[44:45], v[68:69], v[30:31], v[110:111]
	v_cvt_pk_bf16_f32 v46, v30, v31
	v_pk_fma_f32 v[30:31], v[66:67], v[30:31], v[44:45] op_sel:[0,1,0] op_sel_hi:[1,0,1]
	s_nop 0
	v_cvt_pk_bf16_f32 v44, v30, v31
	ds_write2_b32 v102, v46, v44 offset0:80 offset1:148
	s_waitcnt lgkmcnt(7)
	v_pk_fma_f32 v[44:45], v[68:69], v[30:31], v[112:113]
	s_nop 0
	v_pk_fma_f32 v[30:31], v[66:67], v[30:31], v[44:45] op_sel:[0,1,0] op_sel_hi:[1,0,1]
	s_nop 0
	v_pk_fma_f32 v[44:45], v[68:69], v[30:31], v[114:115]
	v_cvt_pk_bf16_f32 v46, v30, v31
	v_pk_fma_f32 v[30:31], v[66:67], v[30:31], v[44:45] op_sel:[0,1,0] op_sel_hi:[1,0,1]
	s_nop 0
	v_cvt_pk_bf16_f32 v44, v30, v31
	ds_write2_b32 v104, v46, v44 offset0:88 offset1:156
	s_waitcnt lgkmcnt(7)
	v_pk_fma_f32 v[44:45], v[68:69], v[30:31], v[116:117]
	s_nop 0
	v_pk_fma_f32 v[30:31], v[66:67], v[30:31], v[44:45] op_sel:[0,1,0] op_sel_hi:[1,0,1]
	s_nop 0
	v_pk_fma_f32 v[44:45], v[68:69], v[30:31], v[118:119]
	v_cvt_pk_bf16_f32 v46, v30, v31
	v_pk_fma_f32 v[30:31], v[66:67], v[30:31], v[44:45] op_sel:[0,1,0] op_sel_hi:[1,0,1]
	s_nop 0
	v_cvt_pk_bf16_f32 v44, v30, v31
	ds_write2_b32 v105, v46, v44 offset0:96 offset1:164
	s_waitcnt lgkmcnt(7)
	v_pk_fma_f32 v[44:45], v[68:69], v[30:31], v[120:121]
	s_nop 0
	v_pk_fma_f32 v[30:31], v[66:67], v[30:31], v[44:45] op_sel:[0,1,0] op_sel_hi:[1,0,1]
	s_nop 0
	v_pk_fma_f32 v[44:45], v[68:69], v[30:31], v[122:123]
	v_cvt_pk_bf16_f32 v46, v30, v31
	v_pk_fma_f32 v[30:31], v[66:67], v[30:31], v[44:45] op_sel:[0,1,0] op_sel_hi:[1,0,1]
	s_nop 0
	v_cvt_pk_bf16_f32 v44, v30, v31
	ds_write2_b32 v106, v46, v44 offset0:104 offset1:172
	s_waitcnt lgkmcnt(7)
	v_pk_fma_f32 v[44:45], v[68:69], v[30:31], v[124:125]
	s_nop 0
	v_pk_fma_f32 v[30:31], v[66:67], v[30:31], v[44:45] op_sel:[0,1,0] op_sel_hi:[1,0,1]
	s_nop 0
	v_pk_fma_f32 v[44:45], v[68:69], v[30:31], v[126:127]
	v_cvt_pk_bf16_f32 v46, v30, v31
	v_pk_fma_f32 v[30:31], v[66:67], v[30:31], v[44:45] op_sel:[0,1,0] op_sel_hi:[1,0,1]
	s_nop 0
	v_cvt_pk_bf16_f32 v44, v30, v31
	ds_write2_b32 v107, v46, v44 offset0:112 offset1:180
	s_waitcnt lgkmcnt(7)
	v_pk_fma_f32 v[44:45], v[68:69], v[30:31], v[128:129]
	s_nop 0
	v_pk_fma_f32 v[30:31], v[66:67], v[30:31], v[44:45] op_sel:[0,1,0] op_sel_hi:[1,0,1]
	s_nop 0
	v_pk_fma_f32 v[44:45], v[68:69], v[30:31], v[130:131]
	v_cvt_pk_bf16_f32 v46, v30, v31
	v_pk_fma_f32 v[82:83], v[66:67], v[30:31], v[44:45] op_sel:[0,1,0] op_sel_hi:[1,0,1]
	s_nop 0
	v_cvt_pk_bf16_f32 v30, v82, v83
	ds_write2_b32 v108, v46, v30 offset0:120 offset1:188
	s_waitcnt lgkmcnt(0)
	ds_read_b128 v[44:47], v88 offset:8448
	ds_read_b128 v[110:113], v88 offset:8512
	s_waitcnt lgkmcnt(1)
	v_mfma_f32_16x16x32_bf16 v[44:47], v[8:11], v[44:47], 0
	s_waitcnt lgkmcnt(0)
	v_mfma_f32_16x16x32_bf16 v[44:47], v[12:15], v[110:113], v[44:47]
	ds_read_b128 v[110:113], v88 offset:8576
	ds_read_b128 v[114:117], v88 offset:8640
	s_waitcnt lgkmcnt(1)
	v_mfma_f32_16x16x32_bf16 v[44:47], v[16:19], v[110:113], v[44:47]
	s_waitcnt lgkmcnt(0)
	v_mfma_f32_16x16x32_bf16 v[44:47], v[20:23], v[114:117], v[44:47]
	s_and_saveexec_b64 s[6:7], s[0:1]
	s_xor_b64 s[6:7], exec, s[6:7]
	v_sub_u32_e32 v28, 0x8ff, v29
	s_andn2_saveexec_b64 s[6:7], s[6:7]
	s_or_b64 exec, exec, s[6:7]
	v_add_u32_e32 v28, v28, v99
	v_ashrrev_i32_e32 v29, 31, v28
	v_lshlrev_b64 v[28:29], 12, v[28:29]
	v_lshl_add_u64 v[28:29], v[4:5], 0, v[28:29]
	global_load_dwordx4 v[28:31], v[28:29], off
	v_lshlrev_b32_e32 v84, 16, v86
	v_and_b32_e32 v85, 0xffff0000, v86
	s_waitcnt vmcnt(5)
	s_cselect_b32 s84, 1, 0
	s_xor_b32 s83, s83, 1
	s_cmp_eq_u32 s83, 0
	s_cbranch_scc1 .Lfq0_0
	s_setprio 1
	s_branch .Lfqe_0

.Lfqe_0:
	s_cmp_eq_u32 s84, 1
	v_pk_add_f32 v[40:41], v[40:41], v[44:45]
	v_lshlrev_b32_e32 v86, 16, v87
	v_and_b32_e32 v87, 0xffff0000, v87
	v_pk_fma_f32 v[40:41], v[0:1], v[84:85], v[40:41]
	v_pk_add_f32 v[42:43], v[42:43], v[46:47]
	v_mul_f32_e32 v44, 0x3d372713, v40
	v_mul_f32_e32 v45, 0x3d372713, v41
	v_pk_fma_f32 v[42:43], v[2:3], v[86:87], v[42:43]
	v_mul_f32_e32 v44, v40, v44
	v_mul_f32_e32 v45, v41, v45
	v_mul_f32_e32 v46, 0x3d372713, v42
	v_mul_f32_e32 v47, 0x3d372713, v43
	v_fma_f32 v44, v40, v44, v40
	v_fma_f32 v45, v41, v45, v41
	v_mul_f32_e32 v46, v42, v46
	v_mul_f32_e32 v47, v43, v47
	v_mul_f32_e32 v44, 0x3f4c422a, v44
	v_mul_f32_e32 v45, 0x3f4c422a, v45
	v_fma_f32 v46, v42, v46, v42
	v_fma_f32 v47, v43, v47, v43
	v_mul_f32_e32 v44, 0x4038aa3b, v44
	v_mul_f32_e32 v45, 0x4038aa3b, v45
	v_mul_f32_e32 v46, 0x3f4c422a, v46
	v_mul_f32_e32 v47, 0x3f4c422a, v47
	v_exp_f32_e32 v44, v44
	v_exp_f32_e32 v45, v45
	v_mul_f32_e32 v46, 0x4038aa3b, v46
	v_mul_f32_e32 v47, 0x4038aa3b, v47
	v_exp_f32_e32 v46, v46
	v_exp_f32_e32 v47, v47
	v_add_f32_e32 v44, 1.0, v44
	v_add_f32_e32 v45, 1.0, v45
	v_rcp_f32_e32 v44, v44
	v_rcp_f32_e32 v45, v45
	v_add_f32_e32 v46, 1.0, v46
	v_add_f32_e32 v47, 1.0, v47
	v_rcp_f32_e32 v46, v46
	v_rcp_f32_e32 v47, v47
	v_pk_add_f32 v[44:45], v[44:45], 1.0 op_sel_hi:[1,0] neg_lo:[1,0] neg_hi:[1,0]
	v_add_u32_e32 v80, v80, v99
	v_pk_mul_f32 v[40:41], v[40:41], v[44:45]
	v_pk_add_f32 v[44:45], v[46:47], 1.0 op_sel_hi:[1,0] neg_lo:[1,0] neg_hi:[1,0]
	v_ashrrev_i32_e32 v81, 31, v80
	v_pk_mul_f32 v[42:43], v[42:43], v[44:45]
	v_cvt_pk_bf16_f32 v40, v40, v41
	v_cvt_pk_bf16_f32 v41, v42, v43
	v_lshlrev_b64 v[42:43], 11, v[80:81]
	v_lshl_add_u64 v[42:43], v[54:55], 0, v[42:43]
	global_store_dwordx2 v[42:43], v[40:41], off
	s_and_saveexec_b64 s[6:7], s[0:1]
	s_xor_b64 s[6:7], exec, s[6:7]
	v_sub_u32_e32 v86, 0x8ef, v103
	s_andn2_saveexec_b64 s[6:7], s[6:7]
	v_add_u32_e32 v86, 16, v89
	s_or_b64 exec, exec, s[6:7]
	s_add_i32 s6, s10, 5
	s_min_u32 s11, s6, 0x8b
	s_add_i32 s11, s11, 4
	v_lshl_or_b32 v41, s11, 4, v97
	s_and_saveexec_b64 s[6:7], s[0:1]
	s_xor_b64 s[6:7], exec, s[6:7]
	v_sub_u32_e32 v42, 0x8ff, v41
	s_or_saveexec_b64 s[6:7], s[6:7]
	v_lshl_add_u32 v40, s11, 4, v90
	s_xor_b64 exec, exec, s[6:7]
	v_lshl_add_u32 v42, s11, 4, v90
	s_or_b64 exec, exec, s[6:7]
	v_add_u32_e32 v42, v42, v99
	v_ashrrev_i32_e32 v43, 31, v42
	v_lshlrev_b64 v[42:43], 5, v[42:43]
	v_lshl_add_u64 v[42:43], v[64:65], 0, v[42:43]
	global_load_dwordx2 v[80:81], v[42:43], off
	v_mfma_f32_16x16x16_bf16 v[44:47], v[70:71], v[60:61], 0
	v_mfma_f32_16x16x16_bf16 v[110:113], v[72:73], v[60:61], 0
	v_mfma_f32_16x16x16_bf16 v[114:117], v[74:75], v[60:61], 0
	s_nop 5
	ds_write_b128 v98, v[44:47]
	v_mfma_f32_16x16x16_bf16 v[118:121], v[76:77], v[60:61], 0
	ds_write_b128 v98, v[110:113] offset:64
	ds_write_b128 v98, v[114:117] offset:128
	s_nop 5
	ds_write_b128 v98, v[118:121] offset:192
	v_mfma_f32_16x16x16_bf16 v[122:125], v[78:79], v[60:61], 0
	v_mfma_f32_16x16x16_bf16 v[42:45], v[48:49], v[60:61], 0
	v_mfma_f32_16x16x16_bf16 v[110:113], v[50:51], v[60:61], 0
	s_nop 5
	ds_write_b128 v98, v[122:125] offset:256
	ds_write_b128 v98, v[42:45] offset:320
	ds_write_b128 v98, v[110:113] offset:384
	v_mfma_f32_16x16x16_bf16 v[42:45], v[52:53], v[60:61], 0
	s_nop 7
	ds_write_b128 v98, v[42:45] offset:448
	s_waitcnt lgkmcnt(0)
	ds_read2_b64 v[42:45], v100 offset1:66
	ds_read2_b64 v[110:113], v100 offset0:132 offset1:198
	ds_read2_b64 v[114:117], v91 offset0:8 offset1:74
	ds_read2_b64 v[118:121], v91 offset0:140 offset1:206
	ds_read2_b64 v[122:125], v92 offset0:16 offset1:82
	ds_read2_b64 v[126:129], v92 offset0:148 offset1:214
	ds_read2_b64 v[130:133], v93 offset0:24 offset1:90
	ds_read2_b64 v[134:137], v93 offset0:156 offset1:222
	s_waitcnt lgkmcnt(7)
	v_pk_fma_f32 v[42:43], v[68:69], v[82:83], v[42:43]
	s_nop 0
	v_pk_fma_f32 v[42:43], v[66:67], v[82:83], v[42:43] op_sel:[0,1,0] op_sel_hi:[1,0,1]
	s_nop 0
	v_pk_fma_f32 v[44:45], v[68:69], v[42:43], v[44:45]
	v_cvt_pk_bf16_f32 v46, v42, v43
	v_pk_fma_f32 v[42:43], v[66:67], v[42:43], v[44:45] op_sel:[0,1,0] op_sel_hi:[1,0,1]
	s_nop 0
	v_cvt_pk_bf16_f32 v44, v42, v43
	ds_write2_b32 v94, v46, v44 offset0:64 offset1:132
	s_waitcnt lgkmcnt(7)
	v_pk_fma_f32 v[44:45], v[68:69], v[42:43], v[110:111]
	s_nop 0
	v_pk_fma_f32 v[42:43], v[66:67], v[42:43], v[44:45] op_sel:[0,1,0] op_sel_hi:[1,0,1]
	s_nop 0
	v_pk_fma_f32 v[44:45], v[68:69], v[42:43], v[112:113]
	v_cvt_pk_bf16_f32 v46, v42, v43
	v_pk_fma_f32 v[42:43], v[66:67], v[42:43], v[44:45] op_sel:[0,1,0] op_sel_hi:[1,0,1]
	s_nop 0
	v_cvt_pk_bf16_f32 v44, v42, v43
	ds_write2_b32 v95, v46, v44 offset0:72 offset1:140
	s_waitcnt lgkmcnt(7)
	v_pk_fma_f32 v[44:45], v[68:69], v[42:43], v[114:115]
	s_nop 0
	v_pk_fma_f32 v[42:43], v[66:67], v[42:43], v[44:45] op_sel:[0,1,0] op_sel_hi:[1,0,1]
	s_nop 0
	v_pk_fma_f32 v[44:45], v[68:69], v[42:43], v[116:117]
	v_cvt_pk_bf16_f32 v46, v42, v43
	v_pk_fma_f32 v[42:43], v[66:67], v[42:43], v[44:45] op_sel:[0,1,0] op_sel_hi:[1,0,1]
	s_nop 0
	v_cvt_pk_bf16_f32 v44, v42, v43
	ds_write2_b32 v102, v46, v44 offset0:80 offset1:148
	s_waitcnt lgkmcnt(7)
	v_pk_fma_f32 v[44:45], v[68:69], v[42:43], v[118:119]
	s_nop 0
	v_pk_fma_f32 v[42:43], v[66:67], v[42:43], v[44:45] op_sel:[0,1,0] op_sel_hi:[1,0,1]
	s_nop 0
	v_pk_fma_f32 v[44:45], v[68:69], v[42:43], v[120:121]
	v_cvt_pk_bf16_f32 v46, v42, v43
	v_pk_fma_f32 v[42:43], v[66:67], v[42:43], v[44:45] op_sel:[0,1,0] op_sel_hi:[1,0,1]
	s_nop 0
	v_cvt_pk_bf16_f32 v44, v42, v43
	ds_write2_b32 v104, v46, v44 offset0:88 offset1:156
	s_waitcnt lgkmcnt(7)
	v_pk_fma_f32 v[44:45], v[68:69], v[42:43], v[122:123]
	s_nop 0
	v_pk_fma_f32 v[42:43], v[66:67], v[42:43], v[44:45] op_sel:[0,1,0] op_sel_hi:[1,0,1]
	s_nop 0
	v_pk_fma_f32 v[44:45], v[68:69], v[42:43], v[124:125]
	v_cvt_pk_bf16_f32 v46, v42, v43
	v_pk_fma_f32 v[42:43], v[66:67], v[42:43], v[44:45] op_sel:[0,1,0] op_sel_hi:[1,0,1]
	s_nop 0
	v_cvt_pk_bf16_f32 v44, v42, v43
	ds_write2_b32 v105, v46, v44 offset0:96 offset1:164
	s_waitcnt lgkmcnt(7)
	v_pk_fma_f32 v[44:45], v[68:69], v[42:43], v[126:127]
	s_nop 0
	v_pk_fma_f32 v[42:43], v[66:67], v[42:43], v[44:45] op_sel:[0,1,0] op_sel_hi:[1,0,1]
	s_nop 0
	v_pk_fma_f32 v[44:45], v[68:69], v[42:43], v[128:129]
	v_cvt_pk_bf16_f32 v46, v42, v43
	v_pk_fma_f32 v[42:43], v[66:67], v[42:43], v[44:45] op_sel:[0,1,0] op_sel_hi:[1,0,1]
	s_nop 0
	v_cvt_pk_bf16_f32 v44, v42, v43
	ds_write2_b32 v106, v46, v44 offset0:104 offset1:172
	s_waitcnt lgkmcnt(7)
	v_pk_fma_f32 v[44:45], v[68:69], v[42:43], v[130:131]
	s_nop 0
	v_pk_fma_f32 v[42:43], v[66:67], v[42:43], v[44:45] op_sel:[0,1,0] op_sel_hi:[1,0,1]
	s_nop 0
	v_pk_fma_f32 v[44:45], v[68:69], v[42:43], v[132:133]
	v_cvt_pk_bf16_f32 v46, v42, v43
	v_pk_fma_f32 v[42:43], v[66:67], v[42:43], v[44:45] op_sel:[0,1,0] op_sel_hi:[1,0,1]
	s_nop 0
	v_cvt_pk_bf16_f32 v44, v42, v43
	ds_write2_b32 v107, v46, v44 offset0:112 offset1:180
	s_waitcnt lgkmcnt(7)
	v_pk_fma_f32 v[44:45], v[68:69], v[42:43], v[134:135]
	s_nop 0
	v_pk_fma_f32 v[42:43], v[66:67], v[42:43], v[44:45] op_sel:[0,1,0] op_sel_hi:[1,0,1]
	s_nop 0
	v_pk_fma_f32 v[44:45], v[68:69], v[42:43], v[136:137]
	v_cvt_pk_bf16_f32 v46, v42, v43
	v_pk_fma_f32 v[84:85], v[66:67], v[42:43], v[44:45] op_sel:[0,1,0] op_sel_hi:[1,0,1]
	s_nop 0
	v_cvt_pk_bf16_f32 v42, v84, v85
	ds_write2_b32 v108, v46, v42 offset0:120 offset1:188
	s_waitcnt lgkmcnt(0)
	ds_read_b128 v[42:45], v88 offset:8448
	ds_read_b128 v[110:113], v88 offset:8512
	s_waitcnt lgkmcnt(1)
	v_mfma_f32_16x16x32_bf16 v[42:45], v[8:11], v[42:45], 0
	s_waitcnt lgkmcnt(0)
	v_mfma_f32_16x16x32_bf16 v[42:45], v[12:15], v[110:113], v[42:45]
	ds_read_b128 v[110:113], v88 offset:8576
	ds_read_b128 v[114:117], v88 offset:8640
	s_waitcnt lgkmcnt(1)
	v_mfma_f32_16x16x32_bf16 v[42:45], v[16:19], v[110:113], v[42:45]
	s_waitcnt lgkmcnt(0)
	v_mfma_f32_16x16x32_bf16 v[44:47], v[20:23], v[114:117], v[42:45]
	s_and_saveexec_b64 s[6:7], s[0:1]
	s_xor_b64 s[6:7], exec, s[6:7]
	v_sub_u32_e32 v40, 0x8ff, v41
	s_andn2_saveexec_b64 s[6:7], s[6:7]
	s_or_b64 exec, exec, s[6:7]
	v_add_u32_e32 v40, v40, v99
	v_ashrrev_i32_e32 v41, 31, v40
	v_lshlrev_b64 v[40:41], 12, v[40:41]
	v_lshl_add_u64 v[40:41], v[4:5], 0, v[40:41]
	global_load_dwordx4 v[40:43], v[40:41], off
	v_add_u32_e32 v82, v86, v99
	v_lshlrev_b32_e32 v86, 16, v60
	v_and_b32_e32 v87, 0xffff0000, v60
	s_waitcnt vmcnt(7)
	s_cselect_b32 s84, 1, 0
	s_xor_b32 s83, s83, 1
	s_cmp_eq_u32 s83, 0
	s_cbranch_scc1 .Lfq0_1
	s_setprio 1
	s_branch .Lfqe_1

.Lfqe_1:
	s_cmp_eq_u32 s84, 1
	v_pk_add_f32 v[36:37], v[36:37], v[44:45]
	v_lshlrev_b32_e32 v60, 16, v61
	v_and_b32_e32 v61, 0xffff0000, v61
	v_pk_fma_f32 v[36:37], v[0:1], v[86:87], v[36:37]
	v_pk_add_f32 v[38:39], v[38:39], v[46:47]
	v_mul_f32_e32 v44, 0x3d372713, v36
	v_mul_f32_e32 v45, 0x3d372713, v37
	v_pk_fma_f32 v[38:39], v[2:3], v[60:61], v[38:39]
	v_mul_f32_e32 v44, v36, v44
	v_mul_f32_e32 v45, v37, v45
	v_mul_f32_e32 v46, 0x3d372713, v38
	v_mul_f32_e32 v47, 0x3d372713, v39
	v_fma_f32 v44, v36, v44, v36
	v_fma_f32 v45, v37, v45, v37
	v_mul_f32_e32 v46, v38, v46
	v_mul_f32_e32 v47, v39, v47
	v_mul_f32_e32 v44, 0x3f4c422a, v44
	v_mul_f32_e32 v45, 0x3f4c422a, v45
	v_fma_f32 v46, v38, v46, v38
	v_fma_f32 v47, v39, v47, v39
	v_mul_f32_e32 v44, 0x4038aa3b, v44
	v_mul_f32_e32 v45, 0x4038aa3b, v45
	v_mul_f32_e32 v46, 0x3f4c422a, v46
	v_mul_f32_e32 v47, 0x3f4c422a, v47
	v_exp_f32_e32 v44, v44
	v_exp_f32_e32 v45, v45
	v_mul_f32_e32 v46, 0x4038aa3b, v46
	v_mul_f32_e32 v47, 0x4038aa3b, v47
	v_exp_f32_e32 v46, v46
	v_exp_f32_e32 v47, v47
	v_add_f32_e32 v44, 1.0, v44
	v_add_f32_e32 v45, 1.0, v45
	v_rcp_f32_e32 v44, v44
	v_rcp_f32_e32 v45, v45
	v_add_f32_e32 v46, 1.0, v46
	v_add_f32_e32 v47, 1.0, v47
	v_rcp_f32_e32 v46, v46
	v_rcp_f32_e32 v47, v47
	v_pk_add_f32 v[44:45], v[44:45], 1.0 op_sel_hi:[1,0] neg_lo:[1,0] neg_hi:[1,0]
	v_ashrrev_i32_e32 v83, 31, v82
	v_pk_mul_f32 v[36:37], v[36:37], v[44:45]
	v_pk_add_f32 v[44:45], v[46:47], 1.0 op_sel_hi:[1,0] neg_lo:[1,0] neg_hi:[1,0]
	v_cvt_pk_bf16_f32 v36, v36, v37
	v_pk_mul_f32 v[38:39], v[38:39], v[44:45]
	s_nop 0
	v_cvt_pk_bf16_f32 v37, v38, v39
	v_lshlrev_b64 v[38:39], 11, v[82:83]
	v_lshl_add_u64 v[38:39], v[54:55], 0, v[38:39]
	global_store_dwordx2 v[38:39], v[36:37], off
	s_and_saveexec_b64 s[6:7], s[0:1]
	s_xor_b64 s[6:7], exec, s[6:7]
	v_sub_u32_e32 v86, 0x8df, v103
	s_andn2_saveexec_b64 s[6:7], s[6:7]
	v_add_u32_e32 v86, 32, v89
	s_or_b64 exec, exec, s[6:7]
	s_add_i32 s6, s10, 6
	s_min_u32 s11, s6, 0x8b
	s_add_i32 s11, s11, 4
	v_lshl_or_b32 v37, s11, 4, v97
	s_and_saveexec_b64 s[6:7], s[0:1]
	s_xor_b64 s[6:7], exec, s[6:7]
	v_sub_u32_e32 v38, 0x8ff, v37
	s_or_saveexec_b64 s[6:7], s[6:7]
	v_lshl_add_u32 v36, s11, 4, v90
	s_xor_b64 exec, exec, s[6:7]
	v_lshl_add_u32 v38, s11, 4, v90
	s_or_b64 exec, exec, s[6:7]
	v_add_u32_e32 v38, v38, v99
	v_ashrrev_i32_e32 v39, 31, v38
	v_lshlrev_b64 v[38:39], 5, v[38:39]
	v_lshl_add_u64 v[38:39], v[64:65], 0, v[38:39]
	global_load_dwordx2 v[82:83], v[38:39], off
	v_mfma_f32_16x16x16_bf16 v[44:47], v[70:71], v[56:57], 0
	v_mfma_f32_16x16x16_bf16 v[110:113], v[72:73], v[56:57], 0
	v_mfma_f32_16x16x16_bf16 v[114:117], v[74:75], v[56:57], 0
	s_nop 5
	ds_write_b128 v98, v[44:47]
	v_mfma_f32_16x16x16_bf16 v[118:121], v[76:77], v[56:57], 0
	ds_write_b128 v98, v[110:113] offset:64
	ds_write_b128 v98, v[114:117] offset:128
	s_nop 5
	ds_write_b128 v98, v[118:121] offset:192
	v_mfma_f32_16x16x16_bf16 v[122:125], v[78:79], v[56:57], 0
	v_mfma_f32_16x16x16_bf16 v[44:47], v[48:49], v[56:57], 0
	v_mfma_f32_16x16x16_bf16 v[110:113], v[50:51], v[56:57], 0
	s_nop 5
	ds_write_b128 v98, v[122:125] offset:256
	ds_write_b128 v98, v[44:47] offset:320
	ds_write_b128 v98, v[110:113] offset:384
	v_mfma_f32_16x16x16_bf16 v[44:47], v[52:53], v[56:57], 0
	s_nop 7
	ds_write_b128 v98, v[44:47] offset:448
	s_waitcnt lgkmcnt(0)
	ds_read2_b64 v[44:47], v100 offset1:66
	ds_read2_b64 v[110:113], v100 offset0:132 offset1:198
	ds_read2_b64 v[114:117], v91 offset0:8 offset1:74
	ds_read2_b64 v[118:121], v91 offset0:140 offset1:206
	ds_read2_b64 v[122:125], v92 offset0:16 offset1:82
	ds_read2_b64 v[126:129], v92 offset0:148 offset1:214
	ds_read2_b64 v[130:133], v93 offset0:24 offset1:90
	ds_read2_b64 v[134:137], v93 offset0:156 offset1:222
	s_waitcnt lgkmcnt(7)
	v_pk_fma_f32 v[38:39], v[68:69], v[84:85], v[44:45]
	s_nop 0
	v_pk_fma_f32 v[38:39], v[66:67], v[84:85], v[38:39] op_sel:[0,1,0] op_sel_hi:[1,0,1]
	s_nop 0
	v_pk_fma_f32 v[44:45], v[68:69], v[38:39], v[46:47]
	v_cvt_pk_bf16_f32 v60, v38, v39
	v_pk_fma_f32 v[38:39], v[66:67], v[38:39], v[44:45] op_sel:[0,1,0] op_sel_hi:[1,0,1]
	s_nop 0
	v_cvt_pk_bf16_f32 v44, v38, v39
	ds_write2_b32 v94, v60, v44 offset0:64 offset1:132
	s_waitcnt lgkmcnt(7)
	v_pk_fma_f32 v[44:45], v[68:69], v[38:39], v[110:111]
	s_nop 0
	v_pk_fma_f32 v[38:39], v[66:67], v[38:39], v[44:45] op_sel:[0,1,0] op_sel_hi:[1,0,1]
	s_nop 0
	v_pk_fma_f32 v[44:45], v[68:69], v[38:39], v[112:113]
	v_cvt_pk_bf16_f32 v46, v38, v39
	v_pk_fma_f32 v[38:39], v[66:67], v[38:39], v[44:45] op_sel:[0,1,0] op_sel_hi:[1,0,1]
	s_nop 0
	v_cvt_pk_bf16_f32 v44, v38, v39
	ds_write2_b32 v95, v46, v44 offset0:72 offset1:140
	s_waitcnt lgkmcnt(7)
	v_pk_fma_f32 v[44:45], v[68:69], v[38:39], v[114:115]
	s_nop 0
	v_pk_fma_f32 v[38:39], v[66:67], v[38:39], v[44:45] op_sel:[0,1,0] op_sel_hi:[1,0,1]
	s_nop 0
	v_pk_fma_f32 v[44:45], v[68:69], v[38:39], v[116:117]
	v_cvt_pk_bf16_f32 v46, v38, v39
	v_pk_fma_f32 v[38:39], v[66:67], v[38:39], v[44:45] op_sel:[0,1,0] op_sel_hi:[1,0,1]
	s_nop 0
	v_cvt_pk_bf16_f32 v44, v38, v39
	ds_write2_b32 v102, v46, v44 offset0:80 offset1:148
	s_waitcnt lgkmcnt(7)
	v_pk_fma_f32 v[44:45], v[68:69], v[38:39], v[118:119]
	s_nop 0
	v_pk_fma_f32 v[38:39], v[66:67], v[38:39], v[44:45] op_sel:[0,1,0] op_sel_hi:[1,0,1]
	s_nop 0
	v_pk_fma_f32 v[44:45], v[68:69], v[38:39], v[120:121]
	v_cvt_pk_bf16_f32 v46, v38, v39
	v_pk_fma_f32 v[38:39], v[66:67], v[38:39], v[44:45] op_sel:[0,1,0] op_sel_hi:[1,0,1]
	s_nop 0
	v_cvt_pk_bf16_f32 v44, v38, v39
	ds_write2_b32 v104, v46, v44 offset0:88 offset1:156
	s_waitcnt lgkmcnt(7)
	v_pk_fma_f32 v[44:45], v[68:69], v[38:39], v[122:123]
	s_nop 0
	v_pk_fma_f32 v[38:39], v[66:67], v[38:39], v[44:45] op_sel:[0,1,0] op_sel_hi:[1,0,1]
	s_nop 0
	v_pk_fma_f32 v[44:45], v[68:69], v[38:39], v[124:125]
	v_cvt_pk_bf16_f32 v46, v38, v39
	v_pk_fma_f32 v[38:39], v[66:67], v[38:39], v[44:45] op_sel:[0,1,0] op_sel_hi:[1,0,1]
	s_nop 0
	v_cvt_pk_bf16_f32 v44, v38, v39
	ds_write2_b32 v105, v46, v44 offset0:96 offset1:164
	s_waitcnt lgkmcnt(7)
	v_pk_fma_f32 v[44:45], v[68:69], v[38:39], v[126:127]
	s_nop 0
	v_pk_fma_f32 v[38:39], v[66:67], v[38:39], v[44:45] op_sel:[0,1,0] op_sel_hi:[1,0,1]
	s_nop 0
	v_pk_fma_f32 v[44:45], v[68:69], v[38:39], v[128:129]
	v_cvt_pk_bf16_f32 v46, v38, v39
	v_pk_fma_f32 v[38:39], v[66:67], v[38:39], v[44:45] op_sel:[0,1,0] op_sel_hi:[1,0,1]
	s_nop 0
	v_cvt_pk_bf16_f32 v44, v38, v39
	ds_write2_b32 v106, v46, v44 offset0:104 offset1:172
	s_waitcnt lgkmcnt(7)
	v_pk_fma_f32 v[44:45], v[68:69], v[38:39], v[130:131]
	s_nop 0
	v_pk_fma_f32 v[38:39], v[66:67], v[38:39], v[44:45] op_sel:[0,1,0] op_sel_hi:[1,0,1]
	s_nop 0
	v_pk_fma_f32 v[44:45], v[68:69], v[38:39], v[132:133]
	v_cvt_pk_bf16_f32 v46, v38, v39
	v_pk_fma_f32 v[38:39], v[66:67], v[38:39], v[44:45] op_sel:[0,1,0] op_sel_hi:[1,0,1]
	s_nop 0
	v_cvt_pk_bf16_f32 v44, v38, v39
	ds_write2_b32 v107, v46, v44 offset0:112 offset1:180
	s_waitcnt lgkmcnt(7)
	v_pk_fma_f32 v[44:45], v[68:69], v[38:39], v[134:135]
	s_nop 0
	v_pk_fma_f32 v[38:39], v[66:67], v[38:39], v[44:45] op_sel:[0,1,0] op_sel_hi:[1,0,1]
	s_nop 0
	v_pk_fma_f32 v[44:45], v[68:69], v[38:39], v[136:137]
	v_cvt_pk_bf16_f32 v46, v38, v39
	v_pk_fma_f32 v[60:61], v[66:67], v[38:39], v[44:45] op_sel:[0,1,0] op_sel_hi:[1,0,1]
	s_nop 0
	v_cvt_pk_bf16_f32 v38, v60, v61
	ds_write2_b32 v108, v46, v38 offset0:120 offset1:188
	s_waitcnt lgkmcnt(0)
	ds_read_b128 v[44:47], v88 offset:8448
	ds_read_b128 v[110:113], v88 offset:8512
	s_waitcnt lgkmcnt(1)
	v_mfma_f32_16x16x32_bf16 v[44:47], v[8:11], v[44:47], 0
	s_waitcnt lgkmcnt(0)
	v_mfma_f32_16x16x32_bf16 v[44:47], v[12:15], v[110:113], v[44:47]
	ds_read_b128 v[110:113], v88 offset:8576
	ds_read_b128 v[114:117], v88 offset:8640
	s_waitcnt lgkmcnt(1)
	v_mfma_f32_16x16x32_bf16 v[44:47], v[16:19], v[110:113], v[44:47]
	s_waitcnt lgkmcnt(0)
	v_mfma_f32_16x16x32_bf16 v[44:47], v[20:23], v[114:117], v[44:47]
	s_and_saveexec_b64 s[6:7], s[0:1]
	s_xor_b64 s[6:7], exec, s[6:7]
	v_sub_u32_e32 v36, 0x8ff, v37
	s_andn2_saveexec_b64 s[6:7], s[6:7]
	s_or_b64 exec, exec, s[6:7]
	v_add_u32_e32 v36, v36, v99
	v_ashrrev_i32_e32 v37, 31, v36
	v_lshlrev_b64 v[36:37], 12, v[36:37]
	v_lshl_add_u64 v[36:37], v[4:5], 0, v[36:37]
	global_load_dwordx4 v[36:39], v[36:37], off
	v_add_u32_e32 v84, v86, v99
	v_lshlrev_b32_e32 v86, 16, v56
	v_and_b32_e32 v87, 0xffff0000, v56
	s_waitcnt vmcnt(9)
	s_cselect_b32 s84, 1, 0
	s_xor_b32 s83, s83, 1
	s_cmp_eq_u32 s83, 0
	s_cbranch_scc1 .Lfq0_2
	s_setprio 1
	s_branch .Lfqe_2

.Lfqe_2:
	s_cmp_eq_u32 s84, 1
	v_pk_add_f32 v[32:33], v[32:33], v[44:45]
	v_lshlrev_b32_e32 v56, 16, v57
	v_and_b32_e32 v57, 0xffff0000, v57
	v_pk_fma_f32 v[32:33], v[0:1], v[86:87], v[32:33]
	v_pk_add_f32 v[34:35], v[34:35], v[46:47]
	v_mul_f32_e32 v44, 0x3d372713, v32
	v_mul_f32_e32 v45, 0x3d372713, v33
	v_pk_fma_f32 v[34:35], v[2:3], v[56:57], v[34:35]
	v_mul_f32_e32 v44, v32, v44
	v_mul_f32_e32 v45, v33, v45
	v_mul_f32_e32 v46, 0x3d372713, v34
	v_mul_f32_e32 v47, 0x3d372713, v35
	v_fma_f32 v44, v32, v44, v32
	v_fma_f32 v45, v33, v45, v33
	v_mul_f32_e32 v46, v34, v46
	v_mul_f32_e32 v47, v35, v47
	v_mul_f32_e32 v44, 0x3f4c422a, v44
	v_mul_f32_e32 v45, 0x3f4c422a, v45
	v_fma_f32 v46, v34, v46, v34
	v_fma_f32 v47, v35, v47, v35
	v_mul_f32_e32 v44, 0x4038aa3b, v44
	v_mul_f32_e32 v45, 0x4038aa3b, v45
	v_mul_f32_e32 v46, 0x3f4c422a, v46
	v_mul_f32_e32 v47, 0x3f4c422a, v47
	v_exp_f32_e32 v44, v44
	v_exp_f32_e32 v45, v45
	v_mul_f32_e32 v46, 0x4038aa3b, v46
	v_mul_f32_e32 v47, 0x4038aa3b, v47
	v_exp_f32_e32 v46, v46
	v_exp_f32_e32 v47, v47
	v_add_f32_e32 v44, 1.0, v44
	v_add_f32_e32 v45, 1.0, v45
	v_rcp_f32_e32 v44, v44
	v_rcp_f32_e32 v45, v45
	v_add_f32_e32 v46, 1.0, v46
	v_add_f32_e32 v47, 1.0, v47
	v_rcp_f32_e32 v46, v46
	v_rcp_f32_e32 v47, v47
	v_pk_add_f32 v[44:45], v[44:45], 1.0 op_sel_hi:[1,0] neg_lo:[1,0] neg_hi:[1,0]
	v_ashrrev_i32_e32 v85, 31, v84
	v_pk_mul_f32 v[32:33], v[32:33], v[44:45]
	v_pk_add_f32 v[44:45], v[46:47], 1.0 op_sel_hi:[1,0] neg_lo:[1,0] neg_hi:[1,0]
	v_cvt_pk_bf16_f32 v32, v32, v33
	v_pk_mul_f32 v[34:35], v[34:35], v[44:45]
	s_nop 0
	v_cvt_pk_bf16_f32 v33, v34, v35
	v_lshlrev_b64 v[34:35], 11, v[84:85]
	v_lshl_add_u64 v[34:35], v[54:55], 0, v[34:35]
	global_store_dwordx2 v[34:35], v[32:33], off
	s_and_saveexec_b64 s[6:7], s[0:1]
	s_xor_b64 s[6:7], exec, s[6:7]
	v_sub_u32_e32 v46, 0x8cf, v103
	s_andn2_saveexec_b64 s[6:7], s[6:7]
	v_add_u32_e32 v46, 48, v89
	s_or_b64 exec, exec, s[6:7]
	s_add_i32 s6, s10, 7
	s_min_u32 s10, s6, 0x8b
	s_add_i32 s10, s10, 4
	v_lshl_or_b32 v56, s10, 4, v97
	s_and_saveexec_b64 s[6:7], s[0:1]
	s_xor_b64 s[6:7], exec, s[6:7]
	v_sub_u32_e32 v32, 0x8ff, v56
	s_or_saveexec_b64 s[6:7], s[6:7]
	v_lshl_add_u32 v47, s10, 4, v90
	s_xor_b64 exec, exec, s[6:7]
	v_lshl_add_u32 v32, s10, 4, v90
	s_or_b64 exec, exec, s[6:7]
	v_add_u32_e32 v32, v32, v99
	v_ashrrev_i32_e32 v33, 31, v32
	v_lshlrev_b64 v[44:45], 5, v[32:33]
	v_lshl_add_u64 v[44:45], v[64:65], 0, v[44:45]
	global_load_dwordx2 v[44:45], v[44:45], off
	v_bfi_b32 v58, s8, v6, v58
	v_bfi_b32 v59, s8, v7, v59
	s_nop 1
	v_mfma_f32_16x16x16_bf16 v[84:87], v[70:71], v[58:59], 0
	v_mfma_f32_16x16x16_bf16 v[110:113], v[72:73], v[58:59], 0
	v_mfma_f32_16x16x16_bf16 v[114:117], v[74:75], v[58:59], 0
	s_nop 5
	ds_write_b128 v98, v[84:87]
	v_mfma_f32_16x16x16_bf16 v[118:121], v[76:77], v[58:59], 0
	ds_write_b128 v98, v[110:113] offset:64
	ds_write_b128 v98, v[114:117] offset:128
	s_nop 5
	ds_write_b128 v98, v[118:121] offset:192
	v_mfma_f32_16x16x16_bf16 v[32:35], v[78:79], v[58:59], 0
	v_mfma_f32_16x16x16_bf16 v[84:87], v[48:49], v[58:59], 0
	v_mfma_f32_16x16x16_bf16 v[110:113], v[50:51], v[58:59], 0
	s_nop 5
	ds_write_b128 v98, v[32:35] offset:256
	ds_write_b128 v98, v[84:87] offset:320
	ds_write_b128 v98, v[110:113] offset:384
	v_mfma_f32_16x16x16_bf16 v[32:35], v[52:53], v[58:59], 0
	s_nop 7
	ds_write_b128 v98, v[32:35] offset:448
	s_waitcnt lgkmcnt(0)
	ds_read2_b64 v[32:35], v100 offset1:66
	ds_read2_b64 v[84:87], v100 offset0:132 offset1:198
	ds_read2_b64 v[110:113], v91 offset0:8 offset1:74
	ds_read2_b64 v[114:117], v91 offset0:140 offset1:206
	ds_read2_b64 v[118:121], v92 offset0:16 offset1:82
	ds_read2_b64 v[122:125], v92 offset0:148 offset1:214
	ds_read2_b64 v[126:129], v93 offset0:24 offset1:90
	ds_read2_b64 v[130:133], v93 offset0:156 offset1:222
	s_waitcnt lgkmcnt(7)
	v_pk_fma_f32 v[32:33], v[68:69], v[60:61], v[32:33]
	s_nop 0
	v_pk_fma_f32 v[32:33], v[66:67], v[60:61], v[32:33] op_sel:[0,1,0] op_sel_hi:[1,0,1]
	s_nop 0
	v_pk_fma_f32 v[34:35], v[68:69], v[32:33], v[34:35]
	v_cvt_pk_bf16_f32 v57, v32, v33
	v_pk_fma_f32 v[32:33], v[66:67], v[32:33], v[34:35] op_sel:[0,1,0] op_sel_hi:[1,0,1]
	s_nop 0
	v_cvt_pk_bf16_f32 v34, v32, v33
	ds_write2_b32 v94, v57, v34 offset0:64 offset1:132
	s_waitcnt lgkmcnt(7)
	v_pk_fma_f32 v[34:35], v[68:69], v[32:33], v[84:85]
	s_nop 0
	v_pk_fma_f32 v[32:33], v[66:67], v[32:33], v[34:35] op_sel:[0,1,0] op_sel_hi:[1,0,1]
	s_nop 0
	v_pk_fma_f32 v[34:35], v[68:69], v[32:33], v[86:87]
	v_cvt_pk_bf16_f32 v57, v32, v33
	v_pk_fma_f32 v[32:33], v[66:67], v[32:33], v[34:35] op_sel:[0,1,0] op_sel_hi:[1,0,1]
	s_nop 0
	v_cvt_pk_bf16_f32 v34, v32, v33
	ds_write2_b32 v95, v57, v34 offset0:72 offset1:140
	s_waitcnt lgkmcnt(7)
	v_pk_fma_f32 v[34:35], v[68:69], v[32:33], v[110:111]
	s_nop 0
	v_pk_fma_f32 v[32:33], v[66:67], v[32:33], v[34:35] op_sel:[0,1,0] op_sel_hi:[1,0,1]
	s_nop 0
	v_pk_fma_f32 v[34:35], v[68:69], v[32:33], v[112:113]
	v_cvt_pk_bf16_f32 v57, v32, v33
	v_pk_fma_f32 v[32:33], v[66:67], v[32:33], v[34:35] op_sel:[0,1,0] op_sel_hi:[1,0,1]
	s_nop 0
	v_cvt_pk_bf16_f32 v34, v32, v33
	ds_write2_b32 v102, v57, v34 offset0:80 offset1:148
	s_waitcnt lgkmcnt(7)
	v_pk_fma_f32 v[34:35], v[68:69], v[32:33], v[114:115]
	s_nop 0
	v_pk_fma_f32 v[32:33], v[66:67], v[32:33], v[34:35] op_sel:[0,1,0] op_sel_hi:[1,0,1]
	s_nop 0
	v_pk_fma_f32 v[34:35], v[68:69], v[32:33], v[116:117]
	v_cvt_pk_bf16_f32 v57, v32, v33
	v_pk_fma_f32 v[32:33], v[66:67], v[32:33], v[34:35] op_sel:[0,1,0] op_sel_hi:[1,0,1]
	s_nop 0
	v_cvt_pk_bf16_f32 v34, v32, v33
	ds_write2_b32 v104, v57, v34 offset0:88 offset1:156
	s_waitcnt lgkmcnt(7)
	v_pk_fma_f32 v[34:35], v[68:69], v[32:33], v[118:119]
	s_nop 0
	v_pk_fma_f32 v[32:33], v[66:67], v[32:33], v[34:35] op_sel:[0,1,0] op_sel_hi:[1,0,1]
	s_nop 0
	v_pk_fma_f32 v[34:35], v[68:69], v[32:33], v[120:121]
	v_cvt_pk_bf16_f32 v57, v32, v33
	v_pk_fma_f32 v[32:33], v[66:67], v[32:33], v[34:35] op_sel:[0,1,0] op_sel_hi:[1,0,1]
	s_nop 0
	v_cvt_pk_bf16_f32 v34, v32, v33
	ds_write2_b32 v105, v57, v34 offset0:96 offset1:164
	s_waitcnt lgkmcnt(7)
	v_pk_fma_f32 v[34:35], v[68:69], v[32:33], v[122:123]
	s_nop 0
	v_pk_fma_f32 v[32:33], v[66:67], v[32:33], v[34:35] op_sel:[0,1,0] op_sel_hi:[1,0,1]
	s_nop 0
	v_pk_fma_f32 v[34:35], v[68:69], v[32:33], v[124:125]
	v_cvt_pk_bf16_f32 v57, v32, v33
	v_pk_fma_f32 v[32:33], v[66:67], v[32:33], v[34:35] op_sel:[0,1,0] op_sel_hi:[1,0,1]
	s_nop 0
	v_cvt_pk_bf16_f32 v34, v32, v33
	ds_write2_b32 v106, v57, v34 offset0:104 offset1:172
	s_waitcnt lgkmcnt(7)
	v_pk_fma_f32 v[34:35], v[68:69], v[32:33], v[126:127]
	s_nop 0
	v_pk_fma_f32 v[32:33], v[66:67], v[32:33], v[34:35] op_sel:[0,1,0] op_sel_hi:[1,0,1]
	s_nop 0
	v_pk_fma_f32 v[34:35], v[68:69], v[32:33], v[128:129]
	v_cvt_pk_bf16_f32 v57, v32, v33
	v_pk_fma_f32 v[32:33], v[66:67], v[32:33], v[34:35] op_sel:[0,1,0] op_sel_hi:[1,0,1]
	s_nop 0
	v_cvt_pk_bf16_f32 v34, v32, v33
	ds_write2_b32 v107, v57, v34 offset0:112 offset1:180
	s_waitcnt lgkmcnt(7)
	v_pk_fma_f32 v[34:35], v[68:69], v[32:33], v[130:131]
	s_nop 0
	v_pk_fma_f32 v[32:33], v[66:67], v[32:33], v[34:35] op_sel:[0,1,0] op_sel_hi:[1,0,1]
	s_nop 0
	v_pk_fma_f32 v[34:35], v[68:69], v[32:33], v[132:133]
	v_cvt_pk_bf16_f32 v57, v32, v33
	v_pk_fma_f32 v[84:85], v[66:67], v[32:33], v[34:35] op_sel:[0,1,0] op_sel_hi:[1,0,1]
	s_nop 0
	v_cvt_pk_bf16_f32 v32, v84, v85
	ds_write2_b32 v108, v57, v32 offset0:120 offset1:188
	s_waitcnt lgkmcnt(0)
	ds_read_b128 v[32:35], v88 offset:8448
	ds_read_b128 v[58:61], v88 offset:8512
	s_waitcnt lgkmcnt(1)
	v_mfma_f32_16x16x32_bf16 v[32:35], v[8:11], v[32:35], 0
	s_waitcnt lgkmcnt(0)
	v_mfma_f32_16x16x32_bf16 v[32:35], v[12:15], v[58:61], v[32:35]
	ds_read_b128 v[58:61], v88 offset:8576
	ds_read_b128 v[92:95], v88 offset:8640
	s_waitcnt lgkmcnt(1)
	v_mfma_f32_16x16x32_bf16 v[32:35], v[16:19], v[58:61], v[32:35]
	s_waitcnt lgkmcnt(0)
	v_mfma_f32_16x16x32_bf16 v[32:35], v[20:23], v[92:95], v[32:35]
	s_and_saveexec_b64 s[6:7], s[0:1]
	s_xor_b64 s[6:7], exec, s[6:7]
	s_cbranch_execz .LBB0_720
	v_sub_u32_e32 v47, 0x8ff, v56
	s_branch .LBB0_720
